# v17 with merge-first role chosen by block id bit 8 instead of bit 3
# speedup vs baseline: 1.0162x; 1.0162x over previous
.LBB0_117:
	s_or_b64 exec, exec, s[52:53]
	s_add_u32 s12, s94, 0x20c0000
	s_addc_u32 s13, s95, 0
	s_add_u32 s0, s94, 0x48e8000
	s_addc_u32 s1, s95, 0
	s_bfe_u32 s14, s64, 0x10008
	v_writelane_b32 v238, s0, 38
	s_cmpk_lt_i32 s64, 0xa00
	s_mov_b32 s97, 0
	v_writelane_b32 v238, s1, 39
	s_cselect_b64 s[0:1], -1, 0
	v_writelane_b32 v238, s0, 40
	s_mov_b32 s3, s97
	v_lshl_add_u64 v[0:1], v[0:1], 2, s[50:51]
	v_writelane_b32 v238, s1, 41
	s_add_u32 s0, s94, 0x130e8000
	s_addc_u32 s1, s95, 0
	v_writelane_b32 v238, s0, 42
	s_waitcnt lgkmcnt(0)
	s_barrier
	v_writelane_b32 v238, s1, 43
	s_add_u32 s0, s94, 0x120e8000
	s_addc_u32 s1, s95, 0
	v_writelane_b32 v238, s0, 44
	v_mov_b32_e32 v216, 0x168e8000
	s_nop 0
	v_writelane_b32 v238, s1, 45
	s_add_u32 s0, s94, 0x110e8000
	s_addc_u32 s1, s95, 0
	s_add_u32 s74, s94, 0xf8e8000
	v_writelane_b32 v238, s0, 46
	s_addc_u32 s75, s95, 0
	v_mov_b32_e32 v217, 0x138e8000
	v_writelane_b32 v238, s1, 47
	s_add_u32 s0, s94, 0xe0e8000
	s_addc_u32 s1, s95, 0
	v_writelane_b32 v238, s0, 48
	v_mov_b32_e32 v165, 0
	v_mov_b32_e32 v218, 1
	v_writelane_b32 v238, s1, 49
	s_add_u32 s0, s94, 0xc8e8000
	s_addc_u32 s1, s95, 0
	v_writelane_b32 v238, s0, 50
	s_cmpk_lt_i32 s64, 0x80
	v_mov_b32_e32 v219, 0x3ecc95a3
	v_writelane_b32 v238, s1, 51
	s_cselect_b64 s[0:1], -1, 0
	v_writelane_b32 v238, s0, 52
	s_add_u32 s15, s94, 0x1e80000
	v_mov_b32_e32 v220, 1.0
	v_writelane_b32 v238, s1, 53
	s_addc_u32 s0, s95, 0
	s_add_u32 s90, s94, 0x24c0000
	s_addc_u32 s91, s95, 0
	v_writelane_b32 v238, s0, 54
	s_add_u32 s0, s94, 0x88e8000
	s_addc_u32 s1, s95, 0
	v_writelane_b32 v238, s0, 55
	s_cmpk_lt_i32 s64, 0x200
	v_mov_b32_e32 v166, 0x12000
	v_writelane_b32 v238, s1, 56
	s_cselect_b64 s[0:1], -1, 0
	s_add_u32 s6, s94, 0x1b148000
	s_addc_u32 s7, s95, 0
	s_add_u32 s85, s94, 0x1b948000
	s_addc_u32 s33, s95, 0
	s_add_u32 s28, s94, 0x1c948000
	v_writelane_b32 v238, s0, 57
	s_addc_u32 s29, s95, 0
	s_lshl_b64 s[34:35], s[2:3], 11
	v_writelane_b32 v238, s1, 58
	s_add_u32 s0, s94, 0x1a00000
	s_addc_u32 s1, s95, 0
	v_writelane_b32 v238, s0, 59
	v_mov_b32_e32 v168, 0x12004
	v_mov_b32_e32 v221, 0xf149f2ca
	v_writelane_b32 v238, s1, 60
	s_add_u32 s0, s94, 0x1800000
	s_addc_u32 s1, s95, 0
	v_writelane_b32 v238, s0, 61
	v_mov_b32_e32 v222, 0x41b17218
	v_mov_b32_e32 v223, 0x7f800000
	v_writelane_b32 v238, s1, 62
	s_add_u32 s0, s94, 0x1700000
	s_addc_u32 s1, s95, 0
	v_writelane_b32 v238, s0, 63
	v_mov_b32_e32 v224, 0x7fc00000
	v_readlane_b32 s48, v238, 20
	v_writelane_b32 v237, s1, 0
	s_add_u32 s0, s94, 0x1500000
	s_addc_u32 s1, s95, 0
	v_writelane_b32 v237, s0, 1
	v_readlane_b32 s54, v238, 26
	v_readlane_b32 s55, v238, 27
	v_writelane_b32 v237, s1, 2
	s_add_u32 s0, s94, 0x1400000
	s_addc_u32 s1, s95, 0
	v_writelane_b32 v237, s0, 3
	v_readlane_b32 s49, v238, 21
	v_readlane_b32 s50, v238, 22
	v_writelane_b32 v237, s1, 4
	s_add_u32 s0, s94, 0x48e1200
	s_addc_u32 s1, s95, 0
	s_add_u32 s8, s94, 0x48e1400
	s_addc_u32 s9, s95, 0
	s_add_u32 s20, s94, 0x48e1500
	s_addc_u32 s21, s95, 0
	s_add_u32 s16, s94, 0x48e1600
	v_writelane_b32 v237, s0, 5
	s_addc_u32 s17, s95, 0
	s_add_u32 s18, s94, 0x48e1700
	v_writelane_b32 v237, s1, 6
	s_mov_b64 s[0:1], 0x1400
	v_lshl_add_u64 v[162:163], v[0:1], 0, s[0:1]
	s_mov_b64 s[0:1], 0x2400
	s_addc_u32 s19, s95, 0
	v_lshl_add_u64 v[160:161], v[0:1], 0, s[0:1]
	s_add_u32 s0, s94, 0x48e1800
	s_addc_u32 s1, s95, 0
	v_writelane_b32 v237, s0, 7
	v_readlane_b32 s51, v238, 23
	v_mbcnt_lo_u32_b32 v0, -1, 0
	v_writelane_b32 v237, s1, 8
	s_add_u32 s0, s94, 0x48e1900
	s_addc_u32 s1, s95, 0
	v_writelane_b32 v237, s0, 9
	v_readlane_b32 s52, v238, 24
	v_readlane_b32 s53, v238, 25
	v_writelane_b32 v237, s1, 10
	s_add_u32 s0, s94, 0x48e1a00
	s_addc_u32 s1, s95, 0
	v_writelane_b32 v237, s0, 11
	v_readlane_b32 s56, v238, 28
	v_readlane_b32 s57, v238, 29
	v_writelane_b32 v237, s1, 12
	s_add_u32 s0, s94, 0x48e1b00
	s_addc_u32 s1, s95, 0
	v_writelane_b32 v237, s0, 13
	v_readlane_b32 s58, v238, 30
	v_readlane_b32 s59, v238, 31
	v_writelane_b32 v237, s1, 14
	s_add_u32 s0, s94, 0x48e1c00
	s_addc_u32 s1, s95, 0
	v_writelane_b32 v237, s0, 15
	v_readlane_b32 s60, v238, 32
	v_readlane_b32 s61, v238, 33
	v_writelane_b32 v237, s1, 16
	s_add_u32 s0, s94, 0x48e1d00
	s_addc_u32 s1, s95, 0
	v_writelane_b32 v237, s0, 17
	v_readlane_b32 s62, v238, 34
	v_readlane_b32 s63, v238, 35
	v_writelane_b32 v237, s1, 18
	s_add_u32 s0, s94, 0x48e1e00
	s_addc_u32 s1, s95, 0
	v_writelane_b32 v237, s0, 19
	v_mbcnt_hi_u32_b32 v215, -1, v0
	v_mov_b32_e32 v225, 0xff800000
	v_writelane_b32 v237, s1, 20
	s_add_u32 s0, s94, 0x48e1f00
	s_addc_u32 s1, s95, 0
	v_writelane_b32 v237, s0, 21
	s_mov_b32 s88, 0xfffffc0
	s_movk_i32 s89, 0x90
	v_writelane_b32 v237, s1, 22
	s_add_u32 s0, s94, 0x48e2000
	s_addc_u32 s1, s95, 0
	v_writelane_b32 v237, s0, 23
	s_movk_i32 s70, 0x210
	s_movk_i32 s71, 0x1800
	v_writelane_b32 v237, s1, 24
	s_add_u32 s0, s94, 0x48e2100
	s_addc_u32 s1, s95, 0
	v_writelane_b32 v237, s0, 25
	s_mov_b32 s26, 0x10000
	s_mov_b32 s27, 0x20000
	v_writelane_b32 v237, s1, 26
	s_add_u32 s0, s94, 0x48e2200
	s_addc_u32 s1, s95, 0
	v_writelane_b32 v237, s0, 27
	s_mov_b32 s84, 0x30000
	s_nop 0
	v_writelane_b32 v237, s1, 28
	s_add_u32 s0, s94, 0x48e2300
	s_addc_u32 s1, s95, 0
	v_writelane_b32 v237, s0, 29
	s_cmp_eq_u32 s30, 0
	s_nop 0
	v_writelane_b32 v237, s1, 30
	s_cselect_b64 s[0:1], -1, 0
	v_writelane_b32 v237, s0, 31
	s_cmp_eq_u32 s30, 1
	s_nop 0
	v_writelane_b32 v237, s1, 32
	s_cselect_b64 s[0:1], -1, 0
	v_writelane_b32 v237, s0, 33
	s_cmp_eq_u32 s30, 2
	s_nop 0
	v_writelane_b32 v237, s1, 34
	s_cselect_b64 s[0:1], -1, 0
	v_writelane_b32 v237, s0, 35
	s_cmp_eq_u32 s30, 3
	s_nop 0
	v_writelane_b32 v237, s1, 36
	s_cselect_b64 s[0:1], -1, 0
	v_writelane_b32 v237, s0, 37
	s_cmp_eq_u32 s30, 4
	s_nop 0
	v_writelane_b32 v237, s1, 38
	s_cselect_b64 s[0:1], -1, 0
	v_writelane_b32 v237, s0, 39
	s_cmp_eq_u32 s30, 5
	s_nop 0
	v_writelane_b32 v237, s1, 40
	s_cselect_b64 s[0:1], -1, 0
	v_writelane_b32 v237, s0, 41
	s_cmp_eq_u32 s30, 6
	s_nop 0
	v_writelane_b32 v237, s1, 42
	s_cselect_b64 s[0:1], -1, 0
	v_writelane_b32 v237, s0, 43
	s_cmp_eq_u32 s30, 7
	s_nop 0
	v_writelane_b32 v237, s1, 44
	s_cselect_b64 s[0:1], -1, 0
	v_writelane_b32 v237, s0, 45
	s_cmp_eq_u32 s30, 8
	s_nop 0
	v_writelane_b32 v237, s1, 46
	s_cselect_b64 s[0:1], -1, 0
	v_writelane_b32 v237, s0, 47
	s_cmp_eq_u32 s30, 9
	s_nop 0
	v_writelane_b32 v237, s1, 48
	s_cselect_b64 s[0:1], -1, 0
	v_writelane_b32 v237, s0, 49
	s_cmp_eq_u32 s30, 10
	s_nop 0
	v_writelane_b32 v237, s1, 50
	s_cselect_b64 s[0:1], -1, 0
	v_writelane_b32 v237, s0, 51
	s_cmp_eq_u32 s30, 11
	s_nop 0
	v_writelane_b32 v237, s1, 52
	s_cselect_b64 s[0:1], -1, 0
	v_writelane_b32 v237, s0, 53
	s_cmp_eq_u32 s30, 12
	s_nop 0
	v_writelane_b32 v237, s1, 54
	s_cselect_b64 s[0:1], -1, 0
	v_writelane_b32 v237, s0, 55
	s_cmp_eq_u32 s30, 13
	s_nop 0
	v_writelane_b32 v237, s1, 56
	s_cselect_b64 s[0:1], -1, 0
	v_writelane_b32 v237, s0, 57
	s_cmp_eq_u32 s30, 14
	s_nop 0
	v_writelane_b32 v237, s1, 58
	s_cselect_b64 s[0:1], -1, 0
	v_writelane_b32 v237, s0, 59
	s_cmp_eq_u32 s30, 15
	s_nop 0
	v_writelane_b32 v237, s1, 60
	s_cselect_b64 s[0:1], -1, 0
	v_writelane_b32 v237, s0, 61
	s_nop 1
	v_writelane_b32 v237, s1, 62
	s_add_u32 s0, s94, 0x48e4400
	s_addc_u32 s1, s95, 0
	v_writelane_b32 v237, s0, 63
	s_nop 1
	v_writelane_b32 v236, s1, 0
	s_add_u32 s0, s94, 0x48e4500
	s_addc_u32 s1, s95, 0
	v_writelane_b32 v236, s0, 1
	s_cmpk_lt_i32 s64, 0x600
	s_nop 0
	v_writelane_b32 v236, s1, 2
	s_cselect_b64 s[0:1], -1, 0
	s_add_u32 s46, s94, 0x198e8000
	v_writelane_b32 v236, s0, 3
	s_addc_u32 s47, s95, 0
	s_nop 0
	v_writelane_b32 v236, s1, 4
	s_add_u32 s0, s94, 0x1b0e8000
	s_addc_u32 s1, s95, 0
	v_writelane_b32 v236, s0, 5
	s_nop 1
	v_writelane_b32 v236, s1, 6
	s_add_u32 s0, s94, 0x1d148000
	v_writelane_b32 v236, s0, 7
	s_addc_u32 s0, s95, 0
	v_writelane_b32 v236, s0, 8
	s_add_u32 s0, s94, 0x1e148000
	v_writelane_b32 v236, s0, 9
	s_addc_u32 s0, s95, 0
	v_writelane_b32 v236, s0, 10
	s_add_u32 s0, s94, 0x2080000
	v_writelane_b32 v236, s0, 11
	s_addc_u32 s0, s95, 0
	v_writelane_b32 v236, s0, 12
	s_add_u32 s0, s94, 0x20a0000
	v_writelane_b32 v236, s0, 13
	s_addc_u32 s0, s95, 0
	v_writelane_b32 v236, s0, 14
	s_add_u32 s0, s94, 0x1f148000
	s_addc_u32 s1, s95, 0
	v_writelane_b32 v236, s0, 15
	s_nop 1
	v_writelane_b32 v236, s1, 16
	s_add_u32 s0, s94, 0x1f1c8000
	v_writelane_b32 v236, s0, 17
	s_addc_u32 s0, s95, 0
	v_writelane_b32 v236, s0, 18
	s_lshl_b32 s0, s64, 8
	v_writelane_b32 v236, s0, 19
	s_lshl_b32 s0, s2, 8
	v_writelane_b32 v236, s0, 20
	s_lshl_b64 s[0:1], s[64:65], 8
	v_writelane_b32 v236, s0, 21
	s_nop 1
	v_writelane_b32 v236, s1, 22
	s_lshl_b64 s[0:1], s[2:3], 8
	v_writelane_b32 v236, s0, 23
	s_nop 1
	v_writelane_b32 v236, s1, 24
	s_lshl_b64 s[0:1], s[64:65], 13
	s_add_u32 s4, s72, s0
	s_addc_u32 s5, s73, s1
	s_add_u32 s4, s4, 0x2000000
	s_addc_u32 s5, s5, 0
	v_writelane_b32 v236, s4, 25
	s_lshl_b64 s[76:77], s[2:3], 13
	s_nop 0
	v_writelane_b32 v236, s5, 26
	s_lshl_b64 s[4:5], s[64:65], 12
	s_add_u32 s24, s94, s4
	s_addc_u32 s25, s95, s5
	s_add_u32 s4, s24, 0x58e8000
	s_addc_u32 s5, s25, 0
	v_writelane_b32 v236, s4, 27
	s_nop 1
	v_writelane_b32 v236, s5, 28
	s_lshl_b64 s[4:5], s[2:3], 12
	s_add_u32 s0, s54, s0
	s_addc_u32 s1, s55, s1
	s_add_u32 s0, s0, 16
	s_addc_u32 s1, s1, 0
	v_writelane_b32 v236, s0, 29
	s_nop 1
	v_writelane_b32 v236, s1, 30
	s_add_u32 s0, s24, 0x1e00000
	s_addc_u32 s1, s25, 0
	v_writelane_b32 v236, s0, 31
	s_lshl_b32 s3, s2, 1
	s_lshl_b32 s24, s2, 6
	v_writelane_b32 v236, s1, 32
	s_lshl_b32 s0, s64, 1
	v_writelane_b32 v236, s0, 33
	s_lshl_b32 s0, s64, 2
	v_writelane_b32 v236, s0, 34
	s_lshl_b32 s0, s64, 6
	v_writelane_b32 v236, s0, 35
	s_mov_b32 s0, s64
	v_writelane_b32 v236, s0, 36
	s_movk_i32 s25, 0x48
	s_nop 0
	v_writelane_b32 v236, s1, 37
	s_lshl_b32 s0, s64, 11
	v_writelane_b32 v236, s0, 38
	s_lshl_b32 s0, s2, 11
	v_writelane_b32 v236, s0, 39
	s_mov_b32 s1, 0
	s_lshl_b32 s0, s2, 2
	v_writelane_b32 v236, s0, 40
	s_nop 1
	v_writelane_b32 v236, s1, 41
	v_writelane_b32 v236, s8, 42
	s_nop 1
	v_writelane_b32 v236, s9, 43
	v_writelane_b32 v236, s20, 44
	s_nop 1
	v_writelane_b32 v236, s21, 45
	v_writelane_b32 v236, s16, 46
	s_nop 1
	v_writelane_b32 v236, s17, 47
	v_writelane_b32 v236, s18, 48
	s_nop 1
	v_writelane_b32 v236, s19, 49
	v_writelane_b32 v236, s14, 50
	v_writelane_b32 v236, s74, 51
	s_nop 1
	v_writelane_b32 v236, s75, 52
	v_writelane_b32 v236, s46, 53
	s_nop 1
	v_writelane_b32 v236, s47, 54
	s_branch .LBB0_121
